# v12 + norm passes de-serialized: phase-1 modulate loads hoisted per row, phase-18 g chunks loaded once before the row loop, per-step vmcnt(0) removed, next-row copies behind one vmcnt(8)
# baseline (speedup 1.0000x reference)
; __device__ __forceinline__ unsigned pk2(float lo, float hi) { return f2bf(lo) | (f2bf(hi) << 16); }
; template <int PH>
; __device__ __forceinline__ void run_phase(const Args& args, LAS unsigned char* lds) {
;     ...
;             for (int row = gw; row < rend; row += NGW) {
;                 const int nrow = row + NGW;
;                 if (nrow < rend) { const float* xn = nrow < ML ? srcL + (size_t)nrow * D : srcC + (size_t)(nrow - ML) * D;
; #pragma unroll
;                     for (int j = 0; j < 8; ++j) nv[j] = ((const f32x4*)xn)[lane + 64 * j]; }
;                 const float* mr = modL + (row < ML ? (row >> 11) : 8) * MODW;
;                 float ss = 0.f;
; #pragma unroll
;                 for (int j = 0; j < 8; ++j) ss += (v[j].x * v[j].x + v[j].y * v[j].y) + (v[j].z * v[j].z + v[j].w * v[j].w);
;                 const float rs = 1.0f / sqrtf(wave_sum(ss) * (1.0f / D) + NEPS);
;                 u32x2* op = (u32x2*)(Hb + (size_t)row * D);
; #pragma unroll
;                 for (int j = 0; j < 8; ++j) { const int c4 = lane + 64 * j; const f32x4 gg = ((const f32x4*)g)[c4], sh = ((const f32x4*)mr)[c4], sc = ((const f32x4*)(mr + D))[c4];
;                     u32x2 w; w.x = pk2(v[j].x * rs * gg.x * (1.f + sc.x) + sh.x, v[j].y * rs * gg.y * (1.f + sc.y) + sh.y);
;                     w.y = pk2(v[j].z * rs * gg.z * (1.f + sc.z) + sh.z, v[j].w * rs * gg.w * (1.f + sc.w) + sh.w); op[c4] = w; }
.LBB0_151:
	s_waitcnt vmcnt(7)
	v_mov_b32_e32 v98, v61
	s_waitcnt vmcnt(6)
	v_mov_b32_e32 v99, v57
	v_mov_b32_e32 v96, v60
	v_mov_b32_e32 v97, v56
	v_pk_mul_f32 v[98:99], v[98:99], v[98:99]
	v_mov_b32_e32 v100, v63
	v_mov_b32_e32 v101, v59
	v_pk_fma_f32 v[96:97], v[96:97], v[96:97], v[98:99]
	v_mov_b32_e32 v98, v62
	v_mov_b32_e32 v99, v58
	v_pk_mul_f32 v[100:101], v[100:101], v[100:101]
	s_waitcnt vmcnt(3)
	v_mul_f32_e32 v80, v44, v44
	v_pk_fma_f32 v[98:99], v[98:99], v[98:99], v[100:101]
	v_pk_mul_f32 v[100:101], v[52:53], v[52:53]
	v_pk_add_f32 v[96:97], v[96:97], v[98:99]
	v_pk_mul_f32 v[98:99], v[54:55], v[54:55]
	v_pk_add_f32 v[96:97], v[96:97], v[96:97] op_sel:[0,1] op_sel_hi:[1,0]
	v_pk_mov_b32 v[102:103], v[100:101], v[98:99] op_sel:[1,0]
	v_mov_b32_e32 v101, v99
	v_pk_add_f32 v[98:99], v[102:103], v[100:101]
	v_mul_f32_e32 v100, v45, v45
	v_pk_add_f32 v[98:99], v[98:99], v[98:99] op_sel:[0,1] op_sel_hi:[1,0]
	v_mov_b32_e32 v97, v80
	v_mov_b32_e32 v99, v100
	v_mul_f32_e32 v80, v49, v49
	v_mul_f32_e32 v101, v46, v46
	v_pk_add_f32 v[96:97], v[96:97], v[98:99]
	v_pk_fma_f32 v[98:99], v[48:49], v[48:49], v[80:81] op_sel_hi:[1,1,0]
	v_mul_f32_e32 v80, v51, v51
	v_mul_f32_e32 v102, v47, v47
	v_mov_b32_e32 v99, v101
	v_pk_fma_f32 v[100:101], v[50:51], v[50:51], v[80:81] op_sel_hi:[1,1,0]
	s_add_i32 s25, s0, s2
	v_mov_b32_e32 v101, v102
	v_pk_add_f32 v[98:99], v[98:99], v[100:101]
	s_waitcnt vmcnt(2)
	v_pk_mul_f32 v[100:101], v[40:41], v[40:41]
	v_pk_add_f32 v[96:97], v[96:97], v[98:99]
	v_pk_mul_f32 v[98:99], v[42:43], v[42:43]
	s_min_i32 s0, s0, 0x4000
	v_pk_mov_b32 v[102:103], v[100:101], v[98:99] op_sel:[1,0]
	v_mov_b32_e32 v101, v99
	v_pk_add_f32 v[98:99], v[102:103], v[100:101]
	s_lshr_b32 s0, s0, 11
	s_waitcnt vmcnt(0)
	v_mul_f32_e32 v80, v0, v0
	v_mul_f32_e32 v100, v1, v1
	v_pk_add_f32 v[96:97], v[96:97], v[96:97] op_sel:[0,1] op_sel_hi:[1,0]
	v_pk_add_f32 v[98:99], v[98:99], v[98:99] op_sel:[0,1] op_sel_hi:[1,0]
	s_mulk_i32 s0, 0x3000
	v_mov_b32_e32 v97, v80
	v_mov_b32_e32 v99, v100
	v_mul_f32_e32 v80, v5, v5
	s_ashr_i32 s1, s0, 31
	v_mul_f32_e32 v101, v2, v2
	v_pk_add_f32 v[96:97], v[96:97], v[98:99]
	v_pk_fma_f32 v[98:99], v[4:5], v[4:5], v[80:81] op_sel_hi:[1,1,0]
	v_mul_f32_e32 v80, v7, v7
	v_mul_f32_e32 v102, v3, v3
	v_mov_b32_e32 v99, v101
	v_pk_fma_f32 v[100:101], v[6:7], v[6:7], v[80:81] op_sel_hi:[1,1,0]
	s_lshl_b64 s[0:1], s[0:1], 2
	v_mov_b32_e32 v101, v102
	s_add_u32 s6, s23, s0
	v_pk_add_f32 v[98:99], v[98:99], v[100:101]
	s_addc_u32 s7, s24, s1
	v_pk_add_f32 v[96:97], v[96:97], v[98:99]
	s_add_u32 s8, s6, 0x2000
	v_add_f32_e32 v80, v96, v97
	global_load_dwordx4 v[96:99], v[68:69], off
	s_addc_u32 s9, s7, 0
	global_load_dwordx4 v[100:103], v95, s[8:9]
	global_load_dwordx4 v[104:107], v95, s[6:7]
	global_load_dwordx4 v[120:123], v[68:69], off offset:1024
	global_load_dwordx4 v[124:127], v87, s[8:9]
	global_load_dwordx4 v[128:131], v95, s[6:7] offset:1024
	global_load_dwordx4 v[132:135], v[68:69], off offset:2048
	global_load_dwordx4 v[136:139], v88, s[8:9]
	global_load_dwordx4 v[140:143], v95, s[6:7] offset:2048
	global_load_dwordx4 v[144:147], v[68:69], off offset:3072
	global_load_dwordx4 v[148:151], v89, s[8:9]
	global_load_dwordx4 v[152:155], v95, s[6:7] offset:3072
	global_load_dwordx4 v[156:159], v[70:71], off
	global_load_dwordx4 v[160:163], v90, s[8:9]
	global_load_dwordx4 v[164:167], v90, s[6:7]
	global_load_dwordx4 v[168:171], v[72:73], off
	global_load_dwordx4 v[172:175], v91, s[8:9]
	global_load_dwordx4 v[176:179], v91, s[6:7]
	global_load_dwordx4 v[180:183], v[74:75], off
	global_load_dwordx4 v[188:191], v92, s[8:9]
	global_load_dwordx4 v[192:195], v92, s[6:7]
	global_load_dwordx4 v[196:199], v[76:77], off
	global_load_dwordx4 v[200:203], v93, s[8:9]
	global_load_dwordx4 v[204:207], v93, s[6:7]
	ds_bpermute_b32 v108, v67, v80
	s_add_u32 s10, s10, s2
	s_addc_u32 s11, s11, s3
	s_cmpk_gt_i32 s25, 0x47ff
	s_waitcnt lgkmcnt(0)
	v_add_f32_e32 v80, v80, v108
	s_nop 1
	v_add_f32_dpp v80, v80, v80 quad_perm:[2,3,0,1] row_mask:0xf bank_mask:0xf
	s_nop 1
	v_add_f32_dpp v80, v80, v80 row_half_mirror row_mask:0xf bank_mask:0xf
	s_nop 1
	v_add_f32_dpp v80, v80, v80 row_mirror row_mask:0xf bank_mask:0xf
	ds_bpermute_b32 v108, v84, v80
	s_waitcnt lgkmcnt(0)
	v_add_f32_e32 v80, v80, v108
	ds_bpermute_b32 v108, v85, v80
	s_waitcnt lgkmcnt(0)
	v_add_f32_e32 v80, v80, v108
	v_fmamk_f32 v80, v80, 0x3a000000, v65
	v_mul_f32_e32 v108, 0x4f800000, v80
	v_cmp_gt_f32_e32 vcc, s14, v80
	s_waitcnt vmcnt(0)
; __device__ __forceinline__ unsigned pk2(float lo, float hi) { return f2bf(lo) | (f2bf(hi) << 16); }
; template <int PH>
; __device__ __forceinline__ void run_phase(const Args& args, LAS unsigned char* lds) {
;     ...
;                 const float rs = 1.0f / sqrtf(wave_sum(ss) * (1.0f / D) + NEPS);
;                 u32x2* op = (u32x2*)(Hb + (size_t)row * D);
; #pragma unroll
;                 for (int j = 0; j < 8; ++j) { const int c4 = lane + 64 * j; const f32x4 gg = ((const f32x4*)g)[c4], sh = ((const f32x4*)mr)[c4], sc = ((const f32x4*)(mr + D))[c4];
;                     u32x2 w; w.x = pk2(v[j].x * rs * gg.x * (1.f + sc.x) + sh.x, v[j].y * rs * gg.y * (1.f + sc.y) + sh.y);
;                     w.y = pk2(v[j].z * rs * gg.z * (1.f + sc.z) + sh.z, v[j].w * rs * gg.w * (1.f + sc.w) + sh.w); op[c4] = w; }
	v_mov_b32_e32 v113, v106
	v_cndmask_b32_e32 v80, v80, v108, vcc
	v_sqrt_f32_e32 v108, v80
	v_mov_b32_e32 v106, v105
	v_mov_b32_e32 v105, v58
	v_mov_b32_e32 v58, v57
	v_add_u32_e32 v109, -1, v108
	v_fma_f32 v110, -v109, v108, v80
	v_cmp_ge_f32_e64 s[0:1], 0, v110
	v_add_u32_e32 v110, 1, v108
	s_nop 0
	v_cndmask_b32_e64 v109, v108, v109, s[0:1]
	v_fma_f32 v108, -v110, v108, v80
	v_cmp_lt_f32_e64 s[0:1], 0, v108
	s_nop 1
	v_cndmask_b32_e64 v108, v109, v110, s[0:1]
	v_mul_f32_e32 v109, 0x37800000, v108
	v_cndmask_b32_e32 v108, v108, v109, vcc
	v_cmp_class_f32_e32 vcc, v80, v86
	s_nop 1
	v_cndmask_b32_e32 v80, v108, v80, vcc
	v_div_scale_f32 v108, s[0:1], v80, v80, 1.0
	v_rcp_f32_e32 v109, v108
	s_mov_b32 s0, s25
	v_fma_f32 v110, -v108, v109, 1.0
	v_fmac_f32_e32 v109, v110, v109
	v_div_scale_f32 v110, vcc, 1.0, v80, 1.0
	v_mul_f32_e32 v111, v110, v109
	v_fma_f32 v112, -v108, v111, v110
	v_fmac_f32_e32 v111, v112, v109
	v_fma_f32 v108, -v108, v111, v110
	v_div_fmas_f32 v108, v108, v109, v111
	v_div_fixup_f32 v80, v108, v80, 1.0
	v_mov_b32_e32 v108, v60
	v_mov_b32_e32 v109, v62
	v_pk_mul_f32 v[108:109], v[108:109], v[80:81] op_sel_hi:[1,0]
	v_mov_b32_e32 v110, v96
	v_mov_b32_e32 v111, v98
	v_mov_b32_e32 v62, v61
	v_pk_mul_f32 v[108:109], v[110:111], v[108:109]
	v_mov_b32_e32 v111, v102
	v_pk_mul_f32 v[60:61], v[62:63], v[80:81] op_sel_hi:[1,0]
	v_mov_b32_e32 v98, v97
	v_mov_b32_e32 v102, v101
	v_mov_b32_e32 v110, v100
	v_pk_mul_f32 v[60:61], v[98:99], v[60:61]
	v_pk_add_f32 v[62:63], v[102:103], 1.0 op_sel_hi:[1,0]
	v_pk_add_f32 v[110:111], v[110:111], 1.0 op_sel_hi:[1,0]
	v_mov_b32_e32 v112, v104
	v_pk_fma_f32 v[60:61], v[62:63], v[60:61], v[106:107]
	v_pk_fma_f32 v[108:109], v[110:111], v[108:109], v[112:113]
	v_and_b32_sdwa v96, v61, v94 dst_sel:DWORD dst_unused:UNUSED_PAD src0_sel:WORD_1 src1_sel:DWORD
	v_and_b32_sdwa v97, v60, v94 dst_sel:DWORD dst_unused:UNUSED_PAD src0_sel:WORD_1 src1_sel:DWORD
	v_and_b32_sdwa v62, v109, v94 dst_sel:DWORD dst_unused:UNUSED_PAD src0_sel:WORD_1 src1_sel:DWORD
	v_and_b32_sdwa v63, v108, v94 dst_sel:DWORD dst_unused:UNUSED_PAD src0_sel:WORD_1 src1_sel:DWORD
	v_add3_u32 v61, v61, v96, s15
	v_add3_u32 v60, v60, v97, s15
	v_add3_u32 v63, v108, v63, s15
	v_add3_u32 v62, v109, v62, s15
	v_and_b32_e32 v61, 0xffff0000, v61
	v_and_b32_e32 v60, 0xffff0000, v60
	v_or_b32_sdwa v61, v61, v62 dst_sel:DWORD dst_unused:UNUSED_PAD src0_sel:DWORD src1_sel:WORD_1
	v_or_b32_sdwa v60, v60, v63 dst_sel:DWORD dst_unused:UNUSED_PAD src0_sel:DWORD src1_sel:WORD_1
	global_store_dwordx2 v[78:79], v[60:61], off offset:-2048
	s_nop 1
	v_mov_b64_e32 v[60:61], v[120:121]
	v_mov_b64_e32 v[62:63], v[122:123]
	s_nop 0
	s_nop 1
	v_mov_b64_e32 v[96:97], v[124:125]
	v_mov_b64_e32 v[98:99], v[126:127]
	s_nop 1
	v_mov_b64_e32 v[100:101], v[128:129]
	v_mov_b64_e32 v[102:103], v[130:131]
	v_mov_b32_e32 v104, v56
	v_pk_mul_f32 v[56:57], v[104:105], v[80:81] op_sel_hi:[1,0]
	v_pk_mul_f32 v[58:59], v[58:59], v[80:81] op_sel_hi:[1,0]
	v_mov_b32_e32 v105, v62
	v_mov_b32_e32 v107, v98
	v_mov_b32_e32 v62, v61
	v_mov_b32_e32 v98, v97
	v_mov_b32_e32 v104, v60
	v_mov_b32_e32 v106, v96
	v_mov_b32_e32 v109, v102
	v_mov_b32_e32 v102, v101
	v_pk_mul_f32 v[58:59], v[62:63], v[58:59]
	v_pk_add_f32 v[62:63], v[98:99], 1.0 op_sel_hi:[1,0]
	v_mov_b32_e32 v108, v100
	v_pk_mul_f32 v[56:57], v[104:105], v[56:57]
	v_pk_add_f32 v[60:61], v[106:107], 1.0 op_sel_hi:[1,0]
	v_pk_fma_f32 v[58:59], v[58:59], v[62:63], v[102:103]
	v_pk_fma_f32 v[56:57], v[56:57], v[60:61], v[108:109]
	v_and_b32_sdwa v62, v59, v94 dst_sel:DWORD dst_unused:UNUSED_PAD src0_sel:WORD_1 src1_sel:DWORD
	v_and_b32_sdwa v63, v58, v94 dst_sel:DWORD dst_unused:UNUSED_PAD src0_sel:WORD_1 src1_sel:DWORD
	v_and_b32_sdwa v60, v57, v94 dst_sel:DWORD dst_unused:UNUSED_PAD src0_sel:WORD_1 src1_sel:DWORD
	v_and_b32_sdwa v61, v56, v94 dst_sel:DWORD dst_unused:UNUSED_PAD src0_sel:WORD_1 src1_sel:DWORD
	v_add3_u32 v59, v59, v62, s15
	v_add3_u32 v58, v58, v63, s15
	v_add3_u32 v56, v56, v61, s15
	v_add3_u32 v57, v57, v60, s15
	v_and_b32_e32 v59, 0xffff0000, v59
	v_and_b32_e32 v58, 0xffff0000, v58
	v_or_b32_sdwa v57, v59, v57 dst_sel:DWORD dst_unused:UNUSED_PAD src0_sel:DWORD src1_sel:WORD_1
	v_or_b32_sdwa v56, v58, v56 dst_sel:DWORD dst_unused:UNUSED_PAD src0_sel:DWORD src1_sel:WORD_1
	global_store_dwordx2 v[78:79], v[56:57], off offset:-1536
	s_nop 1
	v_mov_b64_e32 v[56:57], v[132:133]
	v_mov_b64_e32 v[58:59], v[134:135]
	s_nop 0
	s_nop 1
	v_mov_b64_e32 v[60:61], v[136:137]
	v_mov_b64_e32 v[62:63], v[138:139]
	s_nop 1
	v_mov_b64_e32 v[96:97], v[140:141]
	v_mov_b64_e32 v[98:99], v[142:143]
	v_mov_b32_e32 v100, v52
	v_mov_b32_e32 v101, v54
	v_mov_b32_e32 v54, v53
	v_pk_mul_f32 v[52:53], v[100:101], v[80:81] op_sel_hi:[1,0]
	v_pk_mul_f32 v[54:55], v[54:55], v[80:81] op_sel_hi:[1,0]
	v_mov_b32_e32 v101, v58
	v_mov_b32_e32 v103, v62
	v_mov_b32_e32 v58, v57
	v_mov_b32_e32 v62, v61
	v_mov_b32_e32 v100, v56
	v_mov_b32_e32 v102, v60
	v_mov_b32_e32 v105, v98
	v_mov_b32_e32 v98, v97
	v_pk_mul_f32 v[54:55], v[54:55], v[58:59]
	v_pk_add_f32 v[58:59], v[62:63], 1.0 op_sel_hi:[1,0]
	v_mov_b32_e32 v104, v96
	v_pk_mul_f32 v[52:53], v[52:53], v[100:101]
	v_pk_add_f32 v[56:57], v[102:103], 1.0 op_sel_hi:[1,0]
	v_pk_fma_f32 v[54:55], v[54:55], v[58:59], v[98:99]
	v_pk_fma_f32 v[52:53], v[52:53], v[56:57], v[104:105]
	v_and_b32_sdwa v58, v55, v94 dst_sel:DWORD dst_unused:UNUSED_PAD src0_sel:WORD_1 src1_sel:DWORD
	v_and_b32_sdwa v59, v54, v94 dst_sel:DWORD dst_unused:UNUSED_PAD src0_sel:WORD_1 src1_sel:DWORD
	v_and_b32_sdwa v56, v53, v94 dst_sel:DWORD dst_unused:UNUSED_PAD src0_sel:WORD_1 src1_sel:DWORD
; __device__ __forceinline__ unsigned pk2(float lo, float hi) { return f2bf(lo) | (f2bf(hi) << 16); }
; template <int PH>
; __device__ __forceinline__ void run_phase(const Args& args, LAS unsigned char* lds) {
;     ...
; #pragma unroll
;                 for (int j = 0; j < 8; ++j) { const int c4 = lane + 64 * j; const f32x4 gg = ((const f32x4*)g)[c4], sh = ((const f32x4*)mr)[c4], sc = ((const f32x4*)(mr + D))[c4];
;                     u32x2 w; w.x = pk2(v[j].x * rs * gg.x * (1.f + sc.x) + sh.x, v[j].y * rs * gg.y * (1.f + sc.y) + sh.y);
;                     w.y = pk2(v[j].z * rs * gg.z * (1.f + sc.z) + sh.z, v[j].w * rs * gg.w * (1.f + sc.w) + sh.w); op[c4] = w; }
	v_and_b32_sdwa v57, v52, v94 dst_sel:DWORD dst_unused:UNUSED_PAD src0_sel:WORD_1 src1_sel:DWORD
	v_add3_u32 v55, v55, v58, s15
	v_add3_u32 v54, v54, v59, s15
	v_add3_u32 v52, v52, v57, s15
	v_add3_u32 v53, v53, v56, s15
	v_and_b32_e32 v55, 0xffff0000, v55
	v_and_b32_e32 v54, 0xffff0000, v54
	v_or_b32_sdwa v53, v55, v53 dst_sel:DWORD dst_unused:UNUSED_PAD src0_sel:DWORD src1_sel:WORD_1
	v_or_b32_sdwa v52, v54, v52 dst_sel:DWORD dst_unused:UNUSED_PAD src0_sel:DWORD src1_sel:WORD_1
	global_store_dwordx2 v[78:79], v[52:53], off offset:-1024
	s_nop 1
	v_mov_b64_e32 v[52:53], v[144:145]
	v_mov_b64_e32 v[54:55], v[146:147]
	s_nop 0
	s_nop 1
	v_mov_b64_e32 v[56:57], v[148:149]
	v_mov_b64_e32 v[58:59], v[150:151]
	s_nop 1
	v_mov_b64_e32 v[60:61], v[152:153]
	v_mov_b64_e32 v[62:63], v[154:155]
	v_mov_b32_e32 v96, v48
	v_mov_b32_e32 v97, v50
	v_mov_b32_e32 v50, v49
	v_pk_mul_f32 v[48:49], v[96:97], v[80:81] op_sel_hi:[1,0]
	v_pk_mul_f32 v[50:51], v[50:51], v[80:81] op_sel_hi:[1,0]
	v_mov_b32_e32 v97, v54
	v_mov_b32_e32 v99, v58
	v_mov_b32_e32 v54, v53
	v_mov_b32_e32 v58, v57
	v_mov_b32_e32 v96, v52
	v_mov_b32_e32 v98, v56
	v_mov_b32_e32 v101, v62
	v_mov_b32_e32 v62, v61
	v_pk_mul_f32 v[50:51], v[50:51], v[54:55]
	v_pk_add_f32 v[54:55], v[58:59], 1.0 op_sel_hi:[1,0]
	v_mov_b32_e32 v100, v60
	v_pk_mul_f32 v[48:49], v[48:49], v[96:97]
	v_pk_add_f32 v[52:53], v[98:99], 1.0 op_sel_hi:[1,0]
	v_pk_fma_f32 v[50:51], v[50:51], v[54:55], v[62:63]
	v_pk_fma_f32 v[48:49], v[48:49], v[52:53], v[100:101]
	v_and_b32_sdwa v54, v51, v94 dst_sel:DWORD dst_unused:UNUSED_PAD src0_sel:WORD_1 src1_sel:DWORD
	v_and_b32_sdwa v55, v50, v94 dst_sel:DWORD dst_unused:UNUSED_PAD src0_sel:WORD_1 src1_sel:DWORD
	v_and_b32_sdwa v52, v49, v94 dst_sel:DWORD dst_unused:UNUSED_PAD src0_sel:WORD_1 src1_sel:DWORD
	v_and_b32_sdwa v53, v48, v94 dst_sel:DWORD dst_unused:UNUSED_PAD src0_sel:WORD_1 src1_sel:DWORD
	v_add3_u32 v51, v51, v54, s15
	v_add3_u32 v50, v50, v55, s15
	v_add3_u32 v48, v48, v53, s15
	v_add3_u32 v49, v49, v52, s15
	v_and_b32_e32 v51, 0xffff0000, v51
	v_and_b32_e32 v50, 0xffff0000, v50
	v_or_b32_sdwa v49, v51, v49 dst_sel:DWORD dst_unused:UNUSED_PAD src0_sel:DWORD src1_sel:WORD_1
	v_or_b32_sdwa v48, v50, v48 dst_sel:DWORD dst_unused:UNUSED_PAD src0_sel:DWORD src1_sel:WORD_1
	global_store_dwordx2 v[78:79], v[48:49], off offset:-512
	s_nop 1
	v_mov_b64_e32 v[48:49], v[156:157]
	v_mov_b64_e32 v[50:51], v[158:159]
	s_nop 0
	s_nop 1
	v_mov_b64_e32 v[52:53], v[160:161]
	v_mov_b64_e32 v[54:55], v[162:163]
	s_nop 1
	v_mov_b64_e32 v[56:57], v[164:165]
	v_mov_b64_e32 v[58:59], v[166:167]
	v_mov_b32_e32 v60, v44
	v_mov_b32_e32 v61, v46
	v_mov_b32_e32 v46, v45
	v_pk_mul_f32 v[44:45], v[60:61], v[80:81] op_sel_hi:[1,0]
	v_pk_mul_f32 v[46:47], v[46:47], v[80:81] op_sel_hi:[1,0]
	v_mov_b32_e32 v61, v50
	v_mov_b32_e32 v63, v54
	v_mov_b32_e32 v50, v49
	v_mov_b32_e32 v54, v53
	v_mov_b32_e32 v60, v48
	v_mov_b32_e32 v62, v52
	v_mov_b32_e32 v97, v58
	v_mov_b32_e32 v58, v57
	v_pk_mul_f32 v[46:47], v[46:47], v[50:51]
	v_pk_add_f32 v[50:51], v[54:55], 1.0 op_sel_hi:[1,0]
	v_mov_b32_e32 v96, v56
	v_pk_mul_f32 v[44:45], v[44:45], v[60:61]
	v_pk_add_f32 v[48:49], v[62:63], 1.0 op_sel_hi:[1,0]
	v_pk_fma_f32 v[46:47], v[46:47], v[50:51], v[58:59]
	v_pk_fma_f32 v[44:45], v[44:45], v[48:49], v[96:97]
	v_and_b32_sdwa v50, v47, v94 dst_sel:DWORD dst_unused:UNUSED_PAD src0_sel:WORD_1 src1_sel:DWORD
	v_and_b32_sdwa v51, v46, v94 dst_sel:DWORD dst_unused:UNUSED_PAD src0_sel:WORD_1 src1_sel:DWORD
	v_and_b32_sdwa v48, v45, v94 dst_sel:DWORD dst_unused:UNUSED_PAD src0_sel:WORD_1 src1_sel:DWORD
	v_and_b32_sdwa v49, v44, v94 dst_sel:DWORD dst_unused:UNUSED_PAD src0_sel:WORD_1 src1_sel:DWORD
	v_add3_u32 v47, v47, v50, s15
	v_add3_u32 v46, v46, v51, s15
	v_add3_u32 v44, v44, v49, s15
	v_add3_u32 v45, v45, v48, s15
	v_and_b32_e32 v47, 0xffff0000, v47
	v_and_b32_e32 v46, 0xffff0000, v46
	v_or_b32_sdwa v45, v47, v45 dst_sel:DWORD dst_unused:UNUSED_PAD src0_sel:DWORD src1_sel:WORD_1
	v_or_b32_sdwa v44, v46, v44 dst_sel:DWORD dst_unused:UNUSED_PAD src0_sel:DWORD src1_sel:WORD_1
	global_store_dwordx2 v[78:79], v[44:45], off
	s_nop 1
	v_mov_b64_e32 v[44:45], v[168:169]
	v_mov_b64_e32 v[46:47], v[170:171]
	s_nop 0
	s_nop 1
	v_mov_b64_e32 v[48:49], v[172:173]
	v_mov_b64_e32 v[50:51], v[174:175]
	s_nop 1
	v_mov_b64_e32 v[52:53], v[176:177]
	v_mov_b64_e32 v[54:55], v[178:179]
	v_mov_b32_e32 v56, v40
	v_mov_b32_e32 v57, v42
	v_mov_b32_e32 v42, v41
	v_pk_mul_f32 v[40:41], v[56:57], v[80:81] op_sel_hi:[1,0]
	v_pk_mul_f32 v[42:43], v[42:43], v[80:81] op_sel_hi:[1,0]
	v_mov_b32_e32 v57, v46
	v_mov_b32_e32 v59, v50
	v_mov_b32_e32 v46, v45
	v_mov_b32_e32 v50, v49
	v_mov_b32_e32 v56, v44
	v_mov_b32_e32 v58, v48
	v_mov_b32_e32 v61, v54
	v_mov_b32_e32 v54, v53
	v_pk_mul_f32 v[42:43], v[42:43], v[46:47]
	v_pk_add_f32 v[46:47], v[50:51], 1.0 op_sel_hi:[1,0]
	v_mov_b32_e32 v60, v52
	v_pk_mul_f32 v[40:41], v[40:41], v[56:57]
	v_pk_add_f32 v[44:45], v[58:59], 1.0 op_sel_hi:[1,0]
	v_pk_fma_f32 v[42:43], v[42:43], v[46:47], v[54:55]
; __device__ __forceinline__ unsigned pk2(float lo, float hi) { return f2bf(lo) | (f2bf(hi) << 16); }
; template <int PH>
; __device__ __forceinline__ void run_phase(const Args& args, LAS unsigned char* lds) {
;     ...
; #pragma unroll
;                 for (int j = 0; j < 8; ++j) { const int c4 = lane + 64 * j; const f32x4 gg = ((const f32x4*)g)[c4], sh = ((const f32x4*)mr)[c4], sc = ((const f32x4*)(mr + D))[c4];
;                     u32x2 w; w.x = pk2(v[j].x * rs * gg.x * (1.f + sc.x) + sh.x, v[j].y * rs * gg.y * (1.f + sc.y) + sh.y);
;                     w.y = pk2(v[j].z * rs * gg.z * (1.f + sc.z) + sh.z, v[j].w * rs * gg.w * (1.f + sc.w) + sh.w); op[c4] = w; }
; #pragma unroll
;                 for (int j = 0; j < 8; ++j) v[j] = nv[j];
;             }
	v_pk_fma_f32 v[40:41], v[40:41], v[44:45], v[60:61]
	v_and_b32_sdwa v46, v43, v94 dst_sel:DWORD dst_unused:UNUSED_PAD src0_sel:WORD_1 src1_sel:DWORD
	v_and_b32_sdwa v47, v42, v94 dst_sel:DWORD dst_unused:UNUSED_PAD src0_sel:WORD_1 src1_sel:DWORD
	v_and_b32_sdwa v44, v41, v94 dst_sel:DWORD dst_unused:UNUSED_PAD src0_sel:WORD_1 src1_sel:DWORD
	v_and_b32_sdwa v45, v40, v94 dst_sel:DWORD dst_unused:UNUSED_PAD src0_sel:WORD_1 src1_sel:DWORD
	v_add3_u32 v43, v43, v46, s15
	v_add3_u32 v42, v42, v47, s15
	v_add3_u32 v40, v40, v45, s15
	v_add3_u32 v41, v41, v44, s15
	v_and_b32_e32 v43, 0xffff0000, v43
	v_and_b32_e32 v42, 0xffff0000, v42
	v_or_b32_sdwa v41, v43, v41 dst_sel:DWORD dst_unused:UNUSED_PAD src0_sel:DWORD src1_sel:WORD_1
	v_or_b32_sdwa v40, v42, v40 dst_sel:DWORD dst_unused:UNUSED_PAD src0_sel:DWORD src1_sel:WORD_1
	global_store_dwordx2 v[78:79], v[40:41], off offset:512
	s_nop 1
	v_mov_b64_e32 v[40:41], v[180:181]
	v_mov_b64_e32 v[42:43], v[182:183]
	s_nop 0
	s_nop 1
	v_mov_b64_e32 v[44:45], v[188:189]
	v_mov_b64_e32 v[46:47], v[190:191]
	s_nop 1
	v_mov_b64_e32 v[48:49], v[192:193]
	v_mov_b64_e32 v[50:51], v[194:195]
	v_mov_b32_e32 v52, v4
	v_mov_b32_e32 v53, v6
	v_mov_b32_e32 v6, v5
	v_pk_mul_f32 v[4:5], v[52:53], v[80:81] op_sel_hi:[1,0]
	v_pk_mul_f32 v[6:7], v[6:7], v[80:81] op_sel_hi:[1,0]
	v_mov_b64_e32 v[62:63], v[38:39]
	v_mov_b64_e32 v[60:61], v[36:37]
	v_mov_b32_e32 v53, v42
	v_mov_b32_e32 v55, v46
	v_mov_b32_e32 v42, v41
	v_mov_b32_e32 v46, v45
	v_mov_b32_e32 v52, v40
	v_mov_b32_e32 v54, v44
	v_mov_b32_e32 v57, v50
	v_mov_b32_e32 v50, v49
	v_pk_mul_f32 v[6:7], v[6:7], v[42:43]
	v_pk_add_f32 v[42:43], v[46:47], 1.0 op_sel_hi:[1,0]
	v_mov_b32_e32 v56, v48
	v_pk_mul_f32 v[4:5], v[4:5], v[52:53]
	v_pk_add_f32 v[40:41], v[54:55], 1.0 op_sel_hi:[1,0]
	v_pk_fma_f32 v[6:7], v[6:7], v[42:43], v[50:51]
	v_pk_fma_f32 v[4:5], v[4:5], v[40:41], v[56:57]
	v_and_b32_sdwa v42, v7, v94 dst_sel:DWORD dst_unused:UNUSED_PAD src0_sel:WORD_1 src1_sel:DWORD
	v_and_b32_sdwa v43, v6, v94 dst_sel:DWORD dst_unused:UNUSED_PAD src0_sel:WORD_1 src1_sel:DWORD
	v_and_b32_sdwa v40, v5, v94 dst_sel:DWORD dst_unused:UNUSED_PAD src0_sel:WORD_1 src1_sel:DWORD
	v_and_b32_sdwa v41, v4, v94 dst_sel:DWORD dst_unused:UNUSED_PAD src0_sel:WORD_1 src1_sel:DWORD
	v_add3_u32 v7, v7, v42, s15
	v_add3_u32 v6, v6, v43, s15
	v_add3_u32 v4, v4, v41, s15
	v_add3_u32 v5, v5, v40, s15
	v_and_b32_e32 v7, 0xffff0000, v7
	v_and_b32_e32 v6, 0xffff0000, v6
	v_or_b32_sdwa v5, v7, v5 dst_sel:DWORD dst_unused:UNUSED_PAD src0_sel:DWORD src1_sel:WORD_1
	v_or_b32_sdwa v4, v6, v4 dst_sel:DWORD dst_unused:UNUSED_PAD src0_sel:DWORD src1_sel:WORD_1
	global_store_dwordx2 v[78:79], v[4:5], off offset:1024
	s_nop 1
	v_mov_b64_e32 v[96:97], v[196:197]
	v_mov_b64_e32 v[98:99], v[198:199]
	s_nop 1
	v_mov_b64_e32 v[100:101], v[200:201]
	v_mov_b64_e32 v[102:103], v[202:203]
	s_nop 1
	v_mov_b64_e32 v[104:105], v[204:205]
	v_mov_b64_e32 v[106:107], v[206:207]
	v_mov_b32_e32 v4, v0
	v_mov_b32_e32 v5, v2
	v_mov_b32_e32 v2, v1
	v_pk_mul_f32 v[108:109], v[4:5], v[80:81] op_sel_hi:[1,0]
	v_pk_mul_f32 v[110:111], v[2:3], v[80:81] op_sel_hi:[1,0]
	v_mov_b64_e32 v[58:59], v[34:35]
	v_mov_b64_e32 v[54:55], v[30:31]
	v_mov_b64_e32 v[50:51], v[26:27]
	v_mov_b64_e32 v[46:47], v[22:23]
	v_mov_b64_e32 v[42:43], v[18:19]
	v_mov_b64_e32 v[4:5], v[12:13]
	v_mov_b64_e32 v[0:1], v[8:9]
	v_mov_b64_e32 v[56:57], v[32:33]
	v_mov_b64_e32 v[52:53], v[28:29]
	v_mov_b64_e32 v[48:49], v[24:25]
	v_mov_b64_e32 v[44:45], v[20:21]
	v_mov_b64_e32 v[40:41], v[16:17]
	v_mov_b64_e32 v[6:7], v[14:15]
	v_mov_b64_e32 v[2:3], v[10:11]
	v_mov_b32_e32 v112, v96
	v_mov_b32_e32 v113, v98
	v_mov_b32_e32 v114, v100
	v_mov_b32_e32 v115, v102
	v_mov_b32_e32 v98, v97
	v_mov_b32_e32 v102, v101
	v_mov_b32_e32 v116, v104
	v_mov_b32_e32 v117, v106
	v_mov_b32_e32 v106, v105
	v_pk_mul_f32 v[96:97], v[108:109], v[112:113]
	v_pk_add_f32 v[100:101], v[114:115], 1.0 op_sel_hi:[1,0]
	v_pk_mul_f32 v[98:99], v[110:111], v[98:99]
	v_pk_add_f32 v[102:103], v[102:103], 1.0 op_sel_hi:[1,0]
	v_pk_fma_f32 v[96:97], v[96:97], v[100:101], v[116:117]
	v_pk_fma_f32 v[98:99], v[98:99], v[102:103], v[106:107]
	v_and_b32_sdwa v80, v97, v94 dst_sel:DWORD dst_unused:UNUSED_PAD src0_sel:WORD_1 src1_sel:DWORD
	v_and_b32_sdwa v95, v96, v94 dst_sel:DWORD dst_unused:UNUSED_PAD src0_sel:WORD_1 src1_sel:DWORD
	v_and_b32_sdwa v100, v99, v94 dst_sel:DWORD dst_unused:UNUSED_PAD src0_sel:WORD_1 src1_sel:DWORD
	v_and_b32_sdwa v101, v98, v94 dst_sel:DWORD dst_unused:UNUSED_PAD src0_sel:WORD_1 src1_sel:DWORD
	v_add3_u32 v95, v96, v95, s15
	v_add3_u32 v80, v97, v80, s15
	v_add3_u32 v96, v99, v100, s15
	v_add3_u32 v97, v98, v101, s15
	v_and_b32_e32 v96, 0xffff0000, v96
	v_and_b32_e32 v98, 0xffff0000, v97
	v_or_b32_sdwa v97, v96, v80 dst_sel:DWORD dst_unused:UNUSED_PAD src0_sel:DWORD src1_sel:WORD_1
	v_or_b32_sdwa v96, v98, v95 dst_sel:DWORD dst_unused:UNUSED_PAD src0_sel:DWORD src1_sel:WORD_1
	global_store_dwordx2 v[78:79], v[96:97], off offset:1536
	v_lshl_add_u64 v[78:79], v[78:79], 0, s[4:5]
	s_cbranch_scc1 .LBB0_154

; template <int PH>
; __device__ __forceinline__ void run_phase(const Args& args, LAS unsigned char* lds) {
;     ...
;             const float* g = args.in[36];
;             f32x4 v[8], nv[8];
;             if (gw < ML) {
; #pragma unroll
;                 for (int j = 0; j < 8; ++j) v[j] = ((const f32x4*)(XR + (size_t)gw * D))[lane + 64 * j]; }
;             for (int row = gw; row < ML; row += NGW) {
;                 const int nrow = row + NGW;
;                 if (nrow < ML) {
; #pragma unroll
;                     for (int j = 0; j < 8; ++j) nv[j] = ((const f32x4*)(XR + (size_t)nrow * D))[lane + 64 * j]; }
.LBB0_1776:
	s_cmp_lt_i32 s86, 19
	s_cselect_b64 s[0:1], -1, 0
	s_cmp_gt_i32 s87, 18
	s_cselect_b64 s[2:3], -1, 0
	s_and_b64 s[0:1], s[0:1], s[2:3]
	s_andn2_b64 vcc, exec, s[0:1]
	s_cbranch_vccnz .LBB0_1836
	v_readfirstlane_b32 s0, v184
	s_lshr_b32 s0, s0, 6
	s_lshl_b32 s1, s33, 3
	s_add_i32 s2, s0, s1
	s_cmpk_gt_i32 s2, 0x3fff
	s_cbranch_scc1 .LBB0_1782
	s_ashr_i32 s3, s2, 31
	s_lshl_b32 s4, s88, 3
	s_lshl_b64 s[6:7], s[2:3], 13
	v_and_b32_e32 v0, 63, v184
	s_add_u32 s6, s84, s6
	s_addc_u32 s7, s85, s7
	v_lshlrev_b32_e32 v64, 4, v0
	v_mov_b32_e32 v65, 0
	s_waitcnt lgkmcnt(0)
	v_lshl_add_u64 v[0:1], s[6:7], 0, v[64:65]
	s_mov_b64 s[6:7], 0x6000000
	v_lshl_add_u64 v[4:5], v[0:1], 0, s[6:7]
	v_add_co_u32_e32 v6, vcc, 0x6000000, v0
	global_load_dwordx4 v[56:59], v[4:5], off offset:1024
	global_load_dwordx4 v[48:51], v[4:5], off offset:2048
	v_addc_co_u32_e32 v7, vcc, 0, v1, vcc
	v_add_co_u32_e32 v8, vcc, 0x6001000, v0
	v_mbcnt_lo_u32_b32 v66, -1, 0
	s_nop 0
	v_addc_co_u32_e32 v9, vcc, 0, v1, vcc
	global_load_dwordx4 v[36:39], v[8:9], off offset:2048
	global_load_dwordx4 v[0:3], v[8:9], off offset:3072
	global_load_dwordx4 v[60:63], v[6:7], off
	global_load_dwordx4 v[52:55], v[4:5], off offset:3072
	global_load_dwordx4 v[44:47], v[8:9], off
	global_load_dwordx4 v[40:43], v[8:9], off offset:1024
	v_mbcnt_hi_u32_b32 v78, -1, v66
	s_add_i32 s6, s2, s4
	v_and_b32_e32 v79, 64, v78
	s_ashr_i32 s7, s6, 31
	v_xor_b32_e32 v80, 1, v78
	v_add_u32_e32 v79, 64, v79
	s_lshl_b64 s[6:7], s[6:7], 13
	v_xor_b32_e32 v81, 2, v78
	v_cmp_lt_i32_e32 vcc, v80, v79
	s_add_u32 s6, s84, s6
	v_xor_b32_e32 v82, 4, v78
	v_cndmask_b32_e32 v80, v78, v80, vcc
	v_cmp_lt_i32_e32 vcc, v81, v79
	s_addc_u32 s7, s85, s7
	s_ashr_i32 s5, s4, 31
	v_xor_b32_e32 v83, 8, v78
	v_cndmask_b32_e32 v81, v78, v81, vcc
	v_cmp_lt_i32_e32 vcc, v82, v79
	s_ashr_i32 s10, s1, 31
	s_lshl_b64 s[8:9], s[4:5], 13
	v_xor_b32_e32 v84, 16, v78
	v_cndmask_b32_e32 v82, v78, v82, vcc
	v_cmp_lt_i32_e32 vcc, v83, v79
	s_add_u32 s0, s0, s1
	v_xor_b32_e32 v85, 32, v78
	v_cndmask_b32_e32 v83, v78, v83, vcc
	v_cmp_lt_i32_e32 vcc, v84, v79
	s_addc_u32 s1, 0, s10
	s_lshl_b64 s[0:1], s[0:1], 13
	v_cndmask_b32_e32 v84, v78, v84, vcc
	v_cmp_lt_i32_e32 vcc, v85, v79
	v_mov_b32_e32 v69, v65
	v_mov_b32_e32 v71, v65
	v_mov_b32_e32 v73, v65
	v_mov_b32_e32 v75, v65
	v_or_b32_e32 v68, 0x1000, v64
	v_or_b32_e32 v70, 0x1400, v64
	v_or_b32_e32 v72, 0x1800, v64
	v_or_b32_e32 v74, 0x1c00, v64
	v_cndmask_b32_e32 v85, v78, v85, vcc
	s_add_u32 s10, s82, s0
	s_movk_i32 s3, 0x1000
	v_mov_b32_e32 v76, 0x358637bd
	s_mov_b32 s14, 0xf800000
	v_mov_b32_e32 v77, 0x260
	v_lshl_add_u64 v[66:67], s[80:81], 0, v[64:65]
	v_lshl_add_u64 v[68:69], s[80:81], 0, v[68:69]
	v_lshl_add_u64 v[70:71], s[80:81], 0, v[70:71]
	v_lshl_add_u64 v[72:73], s[80:81], 0, v[72:73]
	v_lshl_add_u64 v[74:75], s[80:81], 0, v[74:75]
	v_lshlrev_b32_e32 v78, 2, v80
	v_lshlrev_b32_e32 v79, 2, v81
	v_lshlrev_b32_e32 v80, 2, v82
	v_lshlrev_b32_e32 v81, 2, v83
	v_lshlrev_b32_e32 v82, 2, v84
	v_lshlrev_b32_e32 v83, 2, v85
	s_addc_u32 s11, s83, s1
	global_load_dwordx4 v[108:111], v[66:67], off
	global_load_dwordx4 v[112:115], v[66:67], off offset:1024
	global_load_dwordx4 v[116:119], v[66:67], off offset:2048
	global_load_dwordx4 v[120:123], v[66:67], off offset:3072
	global_load_dwordx4 v[124:127], v[68:69], off
	global_load_dwordx4 v[128:131], v[70:71], off
	global_load_dwordx4 v[132:135], v[72:73], off
	global_load_dwordx4 v[136:139], v[74:75], off
	s_waitcnt vmcnt(0)
	v_mov_b32_e32 v84, v0
	v_mov_b32_e32 v85, v1
	v_mov_b32_e32 v86, v2
	v_mov_b32_e32 v87, v3
	s_branch .LBB0_1780
; template <int PH>
; __device__ __forceinline__ void run_phase(const Args& args, LAS unsigned char* lds) {
;     ...
;             for (int row = gw; row < ML; row += NGW) {
;                 const int nrow = row + NGW;
;                 if (nrow < ML) {
; #pragma unroll
;                     for (int j = 0; j < 8; ++j) nv[j] = ((const f32x4*)(XR + (size_t)nrow * D))[lane + 64 * j]; }
;                 float ss = 0.f;
; #pragma unroll
;                 for (int j = 0; j < 8; ++j) ss += (v[j].x * v[j].x + v[j].y * v[j].y) + (v[j].z * v[j].z + v[j].w * v[j].w);
;                 const float rs = 1.0f / sqrtf(wave_sum(ss) * (1.0f / D) + NEPS);
;                 f32x4* op = (f32x4*)(args.out + (size_t)row * D);
; #pragma unroll
;                 for (int j = 0; j < 8; ++j) { const f32x4 gg = ((const f32x4*)g)[lane + 64 * j]; op[lane + 64 * j] = v[j] * rs * gg; }
; #pragma unroll
;                 for (int j = 0; j < 8; ++j) v[j] = nv[j];
.LBB0_1779:
	v_pk_mul_f32 v[100:101], v[60:61], v[60:61]
	v_pk_mul_f32 v[102:103], v[56:57], v[56:57]
	v_pk_mul_f32 v[96:97], v[62:63], v[62:63]
	v_pk_mul_f32 v[98:99], v[58:59], v[58:59]
	v_mov_b32_e32 v104, v100
	v_mov_b32_e32 v105, v102
	v_mov_b32_e32 v102, v101
	v_pk_mul_f32 v[92:93], v[50:51], v[50:51]
	v_pk_mul_f32 v[94:95], v[48:49], v[48:49]
	v_pk_add_f32 v[100:101], v[104:105], v[102:103]
	v_mov_b32_e32 v102, v96
	v_mov_b32_e32 v103, v98
	v_mov_b32_e32 v98, v97
	v_pk_add_f32 v[96:97], v[102:103], v[98:99]
	v_pk_mov_b32 v[98:99], v[94:95], v[92:93] op_sel:[1,0]
	v_mov_b32_e32 v95, v93
	v_pk_add_f32 v[92:93], v[98:99], v[94:95]
	v_pk_add_f32 v[96:97], v[100:101], v[96:97]
	v_pk_add_f32 v[92:93], v[92:93], v[92:93] op_sel_hi:[0,1]
	v_mul_f32_e32 v92, v52, v52
	v_pk_fma_f32 v[94:95], v[52:53], v[52:53], v[92:93] op_sel_hi:[1,1,0]
	v_mul_f32_e32 v92, v54, v54
	v_pk_add_f32 v[96:97], v[96:97], v[96:97] op_sel_hi:[0,1]
	v_pk_fma_f32 v[98:99], v[54:55], v[54:55], v[92:93] op_sel_hi:[1,1,0]
	v_mul_f32_e32 v94, v44, v44
	v_mul_f32_e32 v98, v45, v45
	v_mul_f32_e32 v92, v46, v46
	v_mul_f32_e32 v96, v47, v47
	v_pk_mul_f32 v[88:89], v[42:43], v[42:43]
	v_pk_mul_f32 v[90:91], v[40:41], v[40:41]
	v_pk_add_f32 v[94:95], v[94:95], v[98:99]
	v_pk_add_f32 v[92:93], v[92:93], v[96:97]
	s_add_u32 s6, s6, s8
	v_pk_add_f32 v[92:93], v[94:95], v[92:93]
	v_pk_mov_b32 v[94:95], v[90:91], v[88:89] op_sel:[1,0]
	v_mov_b32_e32 v91, v89
	v_pk_add_f32 v[88:89], v[94:95], v[90:91]
	v_pk_add_f32 v[92:93], v[92:93], v[92:93] op_sel_hi:[0,1]
	v_pk_add_f32 v[88:89], v[88:89], v[88:89] op_sel_hi:[0,1]
	v_mul_f32_e32 v88, v36, v36
	v_pk_fma_f32 v[90:91], v[36:37], v[36:37], v[88:89] op_sel_hi:[1,1,0]
	v_mul_f32_e32 v88, v38, v38
	v_pk_fma_f32 v[94:95], v[38:39], v[38:39], v[88:89] op_sel_hi:[1,1,0]
	v_mul_f32_e32 v90, v84, v84
	v_mul_f32_e32 v94, v85, v85
	v_mul_f32_e32 v88, v86, v86
	v_mul_f32_e32 v92, v87, v87
	v_pk_add_f32 v[90:91], v[90:91], v[94:95]
	v_pk_add_f32 v[88:89], v[88:89], v[92:93]
	s_addc_u32 s7, s7, s9
	v_pk_add_f32 v[88:89], v[90:91], v[88:89]
	s_nop 0
	v_add_f32_e32 v88, v88, v89
	s_nop 1
	v_add_f32_dpp v88, v88, v88 quad_perm:[1,0,3,2] row_mask:0xf bank_mask:0xf
	s_nop 1
	v_add_f32_dpp v88, v88, v88 quad_perm:[2,3,0,1] row_mask:0xf bank_mask:0xf
	s_nop 1
	v_add_f32_dpp v88, v88, v88 row_half_mirror row_mask:0xf bank_mask:0xf
	s_nop 1
	v_add_f32_dpp v88, v88, v88 row_mirror row_mask:0xf bank_mask:0xf
	ds_bpermute_b32 v89, v82, v88
	s_waitcnt lgkmcnt(0)
	v_add_f32_e32 v88, v88, v89
	ds_bpermute_b32 v89, v83, v88
	s_waitcnt lgkmcnt(0)
	v_add_f32_e32 v88, v88, v89
	v_fmamk_f32 v88, v88, 0x3a000000, v76
	v_mul_f32_e32 v89, 0x4f800000, v88
	v_cmp_gt_f32_e32 vcc, s14, v88
	s_nop 1
	v_cndmask_b32_e32 v88, v88, v89, vcc
	v_sqrt_f32_e32 v89, v88
	s_nop 0
	v_add_u32_e32 v90, -1, v89
	v_fma_f32 v91, -v90, v89, v88
	v_cmp_ge_f32_e64 s[0:1], 0, v91
	v_add_u32_e32 v91, 1, v89
	s_nop 0
	v_cndmask_b32_e64 v90, v89, v90, s[0:1]
	v_fma_f32 v89, -v91, v89, v88
	v_cmp_lt_f32_e64 s[0:1], 0, v89
	s_nop 1
	v_cndmask_b32_e64 v89, v90, v91, s[0:1]
	v_mul_f32_e32 v90, 0x37800000, v89
	v_cndmask_b32_e32 v89, v89, v90, vcc
	v_cmp_class_f32_e32 vcc, v88, v77
	s_nop 1
	v_cndmask_b32_e32 v88, v89, v88, vcc
	v_div_scale_f32 v89, s[0:1], v88, v88, 1.0
	v_rcp_f32_e32 v90, v89
	s_nop 0
	v_fma_f32 v91, -v89, v90, 1.0
	v_fmac_f32_e32 v90, v91, v90
	v_div_scale_f32 v91, vcc, 1.0, v88, 1.0
	v_mul_f32_e32 v92, v91, v90
	v_fma_f32 v93, -v89, v92, v91
	v_fmac_f32_e32 v92, v93, v90
	v_fma_f32 v89, -v89, v92, v91
	v_div_fmas_f32 v89, v89, v90, v92
	v_div_fixup_f32 v92, v89, v88, 1.0
	v_pk_mul_f32 v[60:61], v[60:61], v[92:93] op_sel_hi:[1,0]
	v_pk_mul_f32 v[62:63], v[62:63], v[92:93] op_sel_hi:[1,0]
	v_pk_mul_f32 v[60:61], v[108:109], v[60:61]
	v_pk_mul_f32 v[62:63], v[110:111], v[62:63]
	v_lshl_add_u64 v[84:85], s[10:11], 0, v[64:65]
	global_store_dwordx4 v[84:85], v[60:63], off
	s_nop 1
	v_pk_mul_f32 v[58:59], v[58:59], v[92:93] op_sel_hi:[1,0]
	v_pk_mul_f32 v[56:57], v[56:57], v[92:93] op_sel_hi:[1,0]
	v_pk_mul_f32 v[50:51], v[50:51], v[92:93] op_sel_hi:[1,0]
	v_pk_mul_f32 v[48:49], v[48:49], v[92:93] op_sel_hi:[1,0]
	v_pk_mul_f32 v[54:55], v[54:55], v[92:93] op_sel_hi:[1,0]
	v_pk_mul_f32 v[52:53], v[52:53], v[92:93] op_sel_hi:[1,0]
	v_add_co_u32_e32 v94, vcc, s3, v84
	v_pk_mul_f32 v[46:47], v[46:47], v[92:93] op_sel_hi:[1,0]
	v_pk_mul_f32 v[44:45], v[44:45], v[92:93] op_sel_hi:[1,0]
	v_addc_co_u32_e32 v95, vcc, 0, v85, vcc
	v_pk_mul_f32 v[42:43], v[42:43], v[92:93] op_sel_hi:[1,0]
	v_pk_mul_f32 v[40:41], v[40:41], v[92:93] op_sel_hi:[1,0]
	v_pk_mul_f32 v[38:39], v[38:39], v[92:93] op_sel_hi:[1,0]
	v_pk_mul_f32 v[36:37], v[36:37], v[92:93] op_sel_hi:[1,0]
	s_add_u32 s10, s10, s8
	v_pk_mul_f32 v[96:97], v[2:3], v[92:93] op_sel_hi:[1,0]
	v_pk_mul_f32 v[92:93], v[0:1], v[92:93] op_sel_hi:[1,0]
	s_addc_u32 s11, s11, s9
	s_andn2_b64 vcc, exec, s[12:13]
	v_pk_mul_f32 v[56:57], v[112:113], v[56:57]
	v_pk_mul_f32 v[58:59], v[114:115], v[58:59]
	global_store_dwordx4 v[84:85], v[56:59], off offset:1024
	s_nop 1
	v_pk_mul_f32 v[48:49], v[116:117], v[48:49]
	v_pk_mul_f32 v[50:51], v[118:119], v[50:51]
	global_store_dwordx4 v[84:85], v[48:51], off offset:2048
	s_nop 1
	v_pk_mul_f32 v[48:49], v[120:121], v[52:53]
	v_pk_mul_f32 v[50:51], v[122:123], v[54:55]
	global_store_dwordx4 v[84:85], v[48:51], off offset:3072
	s_nop 1
	v_pk_mul_f32 v[44:45], v[44:45], v[124:125]
	v_pk_mul_f32 v[46:47], v[46:47], v[126:127]
	global_store_dwordx4 v[94:95], v[44:47], off
	s_nop 1
	v_pk_mul_f32 v[40:41], v[40:41], v[128:129]
	v_pk_mul_f32 v[42:43], v[42:43], v[130:131]
	global_store_dwordx4 v[94:95], v[40:43], off offset:1024
	s_nop 1
	v_pk_mul_f32 v[36:37], v[36:37], v[132:133]
	v_pk_mul_f32 v[38:39], v[38:39], v[134:135]
	global_store_dwordx4 v[94:95], v[36:39], off offset:2048
	s_nop 1
	v_pk_mul_f32 v[88:89], v[92:93], v[136:137]
	v_pk_mul_f32 v[90:91], v[96:97], v[138:139]
	global_store_dwordx4 v[94:95], v[88:91], off offset:3072
	s_waitcnt vmcnt(8)
	v_mov_b64_e32 v[0:1], v[20:21]
	v_mov_b32_e32 v86, v22
	v_mov_b64_e32 v[2:3], v[22:23]
	v_mov_b32_e32 v87, v23
	v_mov_b32_e32 v60, v16
	v_mov_b32_e32 v61, v17
	v_mov_b32_e32 v62, v18
	v_mov_b32_e32 v63, v19
	v_mov_b32_e32 v56, v12
	v_mov_b32_e32 v57, v13
	v_mov_b32_e32 v58, v14
	v_mov_b32_e32 v59, v15
	v_mov_b32_e32 v84, v20
	v_mov_b32_e32 v85, v21
	v_mov_b32_e32 v52, v4
	v_mov_b32_e32 v53, v5
	v_mov_b32_e32 v54, v6
	v_mov_b32_e32 v55, v7
	v_mov_b32_e32 v48, v8
	v_mov_b32_e32 v49, v9
	v_mov_b32_e32 v50, v10
	v_mov_b32_e32 v51, v11
	v_mov_b32_e32 v44, v32
	v_mov_b32_e32 v45, v33
	v_mov_b32_e32 v46, v34
	v_mov_b32_e32 v47, v35
	v_mov_b32_e32 v40, v28
	v_mov_b32_e32 v41, v29
	v_mov_b32_e32 v42, v30
	v_mov_b32_e32 v43, v31
	v_mov_b32_e32 v36, v24
	v_mov_b32_e32 v37, v25
	v_mov_b32_e32 v38, v26
	v_mov_b32_e32 v39, v27
	s_cbranch_vccz .LBB0_1782
